# phase2 scoring loop rewritten: paired permlane reduction, MFMA/VALU software pipelining, direct K-fragment prefetch; phase0 cache conversion loads hoisted
# speedup vs baseline: 1.0303x; 1.0035x over previous
; __device__ void phase0(const Params& p, unsigned char* smem) {
;     ...
;     for (size_t i4 = gtid; i4 < (size_t)8 * 1024 * 512 / 4; i4 += gsz) {
;       const size_t i = i4 * 4;
;       int d = (int)(i & 63), hd = (int)((i >> 6) & 7), j = (int)((i >> 9) & 1023), bs = (int)(i >> 19);
;       const float4 kk4 = *(const float4*)(cka + i);
;       const float4 vv4 = *(const float4*)(cva + i);
;       uint2 ko; ko.x = pack2(kk4.x, kk4.y); ko.y = pack2(kk4.z, kk4.w);
;       *(uint2*)(KAS + ((size_t)(bs * 8 + hd) * 1088 + j) * 64 + d) = ko;
;       u16* vd = VAS + (size_t)(bs * 8 + hd) * 64 * 1088 + (size_t)(j >> 6) * 4096 + d * 64 + (j & 63);
;       vd[0] = f2bf(vv4.x); vd[64] = f2bf(vv4.y); vd[2 * 64] = f2bf(vv4.z); vd[3 * 64] = f2bf(vv4.w);
;     }
.LBB0_193:
	v_lshl_add_u64 v[54:55], v[20:21], 0, v[30:31]
	v_lshl_add_u64 v[52:53], v[28:29], 0, v[30:31]
	global_load_dwordx4 v[44:47], v[54:55], off
	global_load_dwordx4 v[48:51], v[52:53], off
	v_bfe_u32 v15, v40, 4, 3
	v_lshrrev_b32_e32 v39, 14, v40
	v_and_or_b32 v15, v39, 56, v15
	v_bfe_u32 v32, v40, 7, 10
	v_mul_u32_u24_e32 v39, 0x440, v15
	v_and_b32_e32 v43, 60, v16
	v_add_lshl_u32 v32, v39, v32, 7
	v_lshl_add_u64 v[58:59], s[4:5], 0, v[32:33]
	v_lshlrev_b32_e32 v32, 1, v43
	v_and_b32_e32 v60, 0xf00, v10
	v_mad_u64_u32 v[56:57], s[12:13], v15, s0, v[34:35]
	v_lshl_add_u64 v[58:59], v[58:59], 0, v[32:33]
	v_and_b32_e32 v32, 0x1e000, v40
	v_lshrrev_b32_e32 v61, 6, v40
	v_lshl_add_u64 v[56:57], v[56:57], 0, v[32:33]
	v_lshlrev_b32_e32 v32, 1, v60
	v_lshl_add_u64 v[56:57], v[56:57], 0, v[32:33]
	v_and_b32_e32 v32, 0x7e, v61
	v_lshl_add_u64 v[56:57], v[56:57], 0, v[32:33]
	v_lshl_add_u64 v[54:55], v[24:25], 0, v[30:31]
	v_lshl_add_u64 v[52:53], v[26:27], 0, v[30:31]
	v_lshl_add_u64 v[30:31], v[30:31], 0, v[22:23]
	global_load_dwordx4 v[62:65], v[54:55], off
	global_load_dwordx4 v[66:69], v[52:53], off
	s_waitcnt vmcnt(3)
	v_bfe_u32 v15, v44, 16, 1
	s_waitcnt vmcnt(2)
	v_cvt_pk_bf16_f32 v48, v48, v49
	v_cvt_pk_bf16_f32 v49, v50, v51
	v_bfe_u32 v32, v45, 16, 1
	v_bfe_u32 v39, v46, 16, 1
	v_bfe_u32 v43, v47, 16, 1
	v_add3_u32 v15, v44, v15, s1
	global_store_dwordx2 v[58:59], v[48:49], off
	v_add3_u32 v32, v45, v32, s1
	v_add3_u32 v39, v46, v39, s1
	v_add3_u32 v43, v47, v43, s1
	global_store_short_d16_hi v[56:57], v15, off
	global_store_short_d16_hi v[56:57], v32, off offset:128
	global_store_short_d16_hi v[56:57], v39, off offset:256
	global_store_short_d16_hi v[56:57], v43, off offset:384
	v_lshl_add_u64 v[52:53], v[40:41], 0, v[2:3]
	v_add_u32_e32 v39, v9, v40
	v_add_u32_e32 v32, v8, v10
	v_bfe_u32 v40, v52, 4, 3
	v_lshrrev_b32_e32 v41, 14, v52
	v_and_b32_e32 v56, 0xf00, v32
	v_and_or_b32 v32, v41, 56, v40
	v_add_u32_e32 v15, v14, v16
	v_bfe_u32 v43, v39, 7, 10
	v_mul_u32_u24_e32 v58, 0x440, v32
	v_and_b32_e32 v15, 60, v15
	v_mad_u64_u32 v[54:55], s[12:13], v32, s0, v[34:35]
	v_add_lshl_u32 v32, v58, v43, 7
	v_lshl_add_u64 v[40:41], v[52:53], 0, v[2:3]
	v_lshl_add_u64 v[52:53], s[4:5], 0, v[32:33]
	v_lshlrev_b32_e32 v32, 1, v15
	v_lshl_add_u64 v[52:53], v[52:53], 0, v[32:33]
	v_and_b32_e32 v32, 0x1e000, v39
	v_lshrrev_b32_e32 v57, 6, v39
	v_lshl_add_u64 v[54:55], v[54:55], 0, v[32:33]
	v_lshlrev_b32_e32 v32, 1, v56
	v_cmp_lt_u64_e32 vcc, s[10:11], v[40:41]
	v_lshl_add_u64 v[54:55], v[54:55], 0, v[32:33]
	v_and_b32_e32 v32, 0x7e, v57
	v_lshl_add_u64 v[10:11], v[10:11], 0, v[12:13]
	v_lshl_add_u64 v[16:17], v[16:17], 0, v[18:19]
	s_or_b64 s[8:9], vcc, s[8:9]
	v_lshl_add_u64 v[54:55], v[54:55], 0, v[32:33]
	s_waitcnt vmcnt(6)
	v_bfe_u32 v15, v62, 16, 1
	s_waitcnt vmcnt(5)
	v_cvt_pk_bf16_f32 v66, v66, v67
	v_cvt_pk_bf16_f32 v67, v68, v69
	v_bfe_u32 v32, v63, 16, 1
	v_bfe_u32 v39, v64, 16, 1
	v_bfe_u32 v43, v65, 16, 1
	v_add3_u32 v15, v62, v15, s1
	global_store_dwordx2 v[52:53], v[66:67], off
	v_add3_u32 v32, v63, v32, s1
	v_add3_u32 v39, v64, v39, s1
	v_add3_u32 v43, v65, v43, s1
	global_store_short_d16_hi v[54:55], v15, off
	global_store_short_d16_hi v[54:55], v32, off offset:128
	global_store_short_d16_hi v[54:55], v39, off offset:256
	global_store_short_d16_hi v[54:55], v43, off offset:384
	s_andn2_b64 exec, exec, s[8:9]
	s_cbranch_execnz .LBB0_193

; __device__ void phase0(const Params& p, unsigned char* smem) {
;     ...
;     for (size_t i4 = gtid; i4 < (size_t)8 * 512 * 512 / 4; i4 += gsz) {
;       const size_t i = i4 * 4;
;       int d = (int)(i & 63), hd = (int)((i >> 6) & 7), j = (int)((i >> 9) & 511), bs = (int)(i >> 18);
;       const float4 kk4 = *(const float4*)(ckb + i);
;       const float4 vv4 = *(const float4*)(cvb + i);
;       uint2 ko; ko.x = pack2(kk4.x, kk4.y); ko.y = pack2(kk4.z, kk4.w);
;       *(uint2*)(KBS + ((size_t)(bs * 8 + hd) * 576 + j) * 64 + d) = ko;
;       u16* vd = VBS + (size_t)(bs * 8 + hd) * 64 * 576 + (size_t)(j >> 6) * 4096 + d * 64 + (j & 63);
;       vd[0] = f2bf(vv4.x); vd[64] = f2bf(vv4.y); vd[2 * 64] = f2bf(vv4.z); vd[3 * 64] = f2bf(vv4.w);
;     }
.LBB0_206:
	v_lshl_add_u64 v[46:47], v[18:19], 0, v[28:29]
	v_lshl_add_u64 v[34:35], v[26:27], 0, v[28:29]
	global_load_dwordx4 v[38:41], v[46:47], off
	global_load_dwordx4 v[42:45], v[34:35], off
	v_bfe_u32 v7, v4, 4, 3
	v_lshrrev_b32_e32 v30, 13, v4
	v_and_or_b32 v7, v30, 56, v7
	v_bfe_u32 v13, v4, 7, 9
	v_mul_u32_u24_e32 v30, 0x240, v7
	v_and_b32_e32 v37, 60, v14
	v_add_lshl_u32 v30, v30, v13, 7
	v_lshl_add_u64 v[50:51], s[4:5], 0, v[30:31]
	v_lshlrev_b32_e32 v30, 1, v37
	v_and_b32_e32 v52, 0xf00, v8
	v_mad_u64_u32 v[48:49], s[12:13], v7, s0, v[32:33]
	v_lshl_add_u64 v[50:51], v[50:51], 0, v[30:31]
	v_and_b32_e32 v30, 0xe000, v4
	v_lshrrev_b32_e32 v53, 6, v4
	v_lshl_add_u64 v[48:49], v[48:49], 0, v[30:31]
	v_lshlrev_b32_e32 v30, 1, v52
	v_lshl_add_u64 v[48:49], v[48:49], 0, v[30:31]
	v_and_b32_e32 v30, 0x7e, v53
	v_lshl_add_u64 v[48:49], v[48:49], 0, v[30:31]
	v_lshl_add_u64 v[46:47], v[22:23], 0, v[28:29]
	v_lshl_add_u64 v[34:35], v[24:25], 0, v[28:29]
	v_lshl_add_u64 v[28:29], v[28:29], 0, v[20:21]
	global_load_dwordx4 v[62:65], v[46:47], off
	global_load_dwordx4 v[66:69], v[34:35], off
	s_waitcnt vmcnt(3)
	v_bfe_u32 v7, v38, 16, 1
	s_waitcnt vmcnt(2)
	v_cvt_pk_bf16_f32 v42, v42, v43
	v_cvt_pk_bf16_f32 v43, v44, v45
	v_bfe_u32 v13, v39, 16, 1
	v_bfe_u32 v30, v40, 16, 1
	v_bfe_u32 v37, v41, 16, 1
	v_add3_u32 v7, v38, v7, s1
	global_store_dwordx2 v[50:51], v[42:43], off
	v_add3_u32 v13, v39, v13, s1
	v_add3_u32 v30, v40, v30, s1
	v_add3_u32 v37, v41, v37, s1
	global_store_short_d16_hi v[48:49], v7, off
	global_store_short_d16_hi v[48:49], v13, off offset:128
	global_store_short_d16_hi v[48:49], v30, off offset:256
	global_store_short_d16_hi v[48:49], v37, off offset:384
	v_lshl_add_u64 v[34:35], v[4:5], 0, v[2:3]
	v_add_u32_e32 v7, v1, v4
	v_add_u32_e32 v4, v6, v8
	v_bfe_u32 v13, v34, 4, 3
	v_lshrrev_b32_e32 v37, 13, v34
	v_and_b32_e32 v49, 0xf00, v4
	v_and_or_b32 v4, v37, 56, v13
	v_add_u32_e32 v5, v12, v14
	v_bfe_u32 v30, v7, 7, 9
	v_mul_u32_u24_e32 v13, 0x240, v4
	v_and_b32_e32 v48, 60, v5
	v_add_lshl_u32 v30, v13, v30, 7
	v_mad_u64_u32 v[46:47], s[12:13], v4, s0, v[32:33]
	v_lshl_add_u64 v[4:5], v[34:35], 0, v[2:3]
	v_lshl_add_u64 v[34:35], s[4:5], 0, v[30:31]
	v_lshlrev_b32_e32 v30, 1, v48
	v_lshl_add_u64 v[34:35], v[34:35], 0, v[30:31]
	v_and_b32_e32 v30, 0xe000, v7
	v_lshrrev_b32_e32 v50, 6, v7
	v_lshl_add_u64 v[46:47], v[46:47], 0, v[30:31]
	v_lshlrev_b32_e32 v30, 1, v49
	v_cmp_lt_u64_e32 vcc, s[10:11], v[4:5]
	v_lshl_add_u64 v[46:47], v[46:47], 0, v[30:31]
	v_and_b32_e32 v30, 0x7e, v50
	v_lshl_add_u64 v[8:9], v[8:9], 0, v[10:11]
	v_lshl_add_u64 v[14:15], v[14:15], 0, v[16:17]
	s_or_b64 s[8:9], vcc, s[8:9]
	v_lshl_add_u64 v[46:47], v[46:47], 0, v[30:31]
	s_waitcnt vmcnt(6)
	v_bfe_u32 v7, v62, 16, 1
	s_waitcnt vmcnt(5)
	v_cvt_pk_bf16_f32 v66, v66, v67
	v_cvt_pk_bf16_f32 v67, v68, v69
	v_bfe_u32 v13, v63, 16, 1
	v_bfe_u32 v30, v64, 16, 1
	v_bfe_u32 v37, v65, 16, 1
	v_add3_u32 v7, v62, v7, s1
	global_store_dwordx2 v[34:35], v[66:67], off
	v_add3_u32 v13, v63, v13, s1
	v_add3_u32 v30, v64, v30, s1
	v_add3_u32 v34, v65, v37, s1
	global_store_short_d16_hi v[46:47], v7, off
	global_store_short_d16_hi v[46:47], v13, off offset:128
	global_store_short_d16_hi v[46:47], v30, off offset:256
	global_store_short_d16_hi v[46:47], v34, off offset:384
	s_andn2_b64 exec, exec, s[8:9]
	s_cbranch_execnz .LBB0_206

; __device__ void phase2(const Params& p, unsigned char* smem) {
;     ...
;     {
;       const int nchunk = nvis >> 6;
;       const u16* kbase = KI + (size_t)n16 * 64 + 8 * g4;
;       bf16x8 nA0, nB0, nA1, nB1, nA2, nB2, nA3, nB3;
;       int c = wave;
;       if (c < nchunk) P2_LOADCHUNK(c, nA0, nB0, nA1, nB1, nA2, nB2, nA3, nB3)
;       for (; c < nchunk; c += 8) {
;         bf16x8 cA0 = nA0, cB0 = nB0, cA1 = nA1, cB1 = nB1, cA2 = nA2, cB2 = nB2, cA3 = nA3, cB3 = nB3;
;         if (c + 8 < nchunk) P2_LOADCHUNK(c + 8, nA0, nB0, nA1, nB1, nA2, nB2, nA3, nB3)
;         __builtin_amdgcn_sched_barrier(0);
;         P2_SCORE(cA0, cB0, c * 4 + 0)
;         P2_SCORE(cA1, cB1, c * 4 + 1)
;         P2_SCORE(cA2, cB2, c * 4 + 2)
;         P2_SCORE(cA3, cB3, c * 4 + 3)
;       }
.LBB0_548:
	s_or_b64 exec, exec, s[38:39]
	s_and_saveexec_b64 s[38:39], s[36:37]
	s_cbranch_execz .LBB0_554
	s_waitcnt vmcnt(0)
	v_readfirstlane_b32 s40, v133
	v_lshl_add_u64 v[142:143], s[48:49], 0, v[134:135]
	v_lshrrev_b32_e32 v202, 4, v154
	v_and_b32_e32 v203, 1, v202
	v_lshrrev_b32_e32 v204, 1, v202
	v_lshl_or_b32 v203, v203, 1, v204
	v_lshlrev_b32_e32 v203, 14, v203
	v_and_b32_e32 v204, 15, v154
	v_lshl_or_b32 v210, v204, 1, v203
	v_lshl_add_u32 v210, v133, 7, v210
	v_add_co_u32_e32 v208, vcc, 0x1000, v142
	v_add_u32_e32 v211, 0x10000, v210
	v_addc_co_u32_e32 v209, vcc, 0, v143, vcc
	s_add_i32 s41, s40, 8
.Lsc_loop:
	s_cmp_lt_u32 s41, s47
	s_cselect_b64 vcc, 0, -1
	s_waitcnt vmcnt(6)
	v_mfma_f32_16x16x32_bf16 v[168:171], v[38:41], v[34:37], 0
	v_mfma_f32_16x16x32_bf16 v[172:175], v[50:53], v[34:37], 0
	v_mfma_f32_16x16x32_bf16 v[176:179], v[62:65], v[34:37], 0
	v_mfma_f32_16x16x32_bf16 v[180:183], v[74:77], v[34:37], 0
	v_mfma_f32_16x16x32_bf16 v[168:171], v[42:45], v[30:33], v[168:171]
	v_mfma_f32_16x16x32_bf16 v[172:175], v[54:57], v[30:33], v[172:175]
	v_mfma_f32_16x16x32_bf16 v[176:179], v[66:69], v[30:33], v[176:179]
	v_mfma_f32_16x16x32_bf16 v[180:183], v[78:81], v[30:33], v[180:183]
	s_cbranch_vccnz .Lsc_np0
	global_load_dwordx4 v[34:37], v[142:143], off
	global_load_dwordx4 v[30:33], v[142:143], off offset:64
	s_branch .Lsc_c0

; __device__ void phase2(const Params& p, unsigned char* smem) {
;     ...
;       for (; c < nchunk; c += 8) {
;         bf16x8 cA0 = nA0, cB0 = nB0, cA1 = nA1, cB1 = nB1, cA2 = nA2, cB2 = nB2, cA3 = nA3, cB3 = nB3;
;         if (c + 8 < nchunk) P2_LOADCHUNK(c + 8, nA0, nB0, nA1, nB1, nA2, nB2, nA3, nB3)
;         __builtin_amdgcn_sched_barrier(0);
;         P2_SCORE(cA0, cB0, c * 4 + 0)
;         P2_SCORE(cA1, cB1, c * 4 + 1)
;         P2_SCORE(cA2, cB2, c * 4 + 2)
;         P2_SCORE(cA3, cB3, c * 4 + 3)
;       }
.Lsc_c0:
	s_waitcnt vmcnt(6)
	v_mfma_f32_16x16x32_bf16 v[184:187], v[38:41], v[26:29], 0
	v_mfma_f32_16x16x32_bf16 v[188:191], v[50:53], v[26:29], 0
	v_mfma_f32_16x16x32_bf16 v[192:195], v[62:65], v[26:29], 0
	v_mfma_f32_16x16x32_bf16 v[196:199], v[74:77], v[26:29], 0
	v_mfma_f32_16x16x32_bf16 v[184:187], v[42:45], v[22:25], v[184:187]
	v_mfma_f32_16x16x32_bf16 v[188:191], v[54:57], v[22:25], v[188:191]
	v_mfma_f32_16x16x32_bf16 v[192:195], v[66:69], v[22:25], v[192:195]
	v_mfma_f32_16x16x32_bf16 v[196:199], v[78:81], v[22:25], v[196:199]
	s_cbranch_vccnz .Lsc_np1
	global_load_dwordx4 v[26:29], v[142:143], off offset:2048
	global_load_dwordx4 v[22:25], v[142:143], off offset:2112
	s_branch .Lsc_c1

.Lsc_c1:
	v_max_f32_e32 v169, 0, v169
	v_max_f32_e32 v168, 0, v168
	v_mul_f32_e32 v169, v47, v169
	v_max_f32_e32 v170, 0, v170
	v_fmac_f32_e32 v169, v46, v168
	v_max_f32_e32 v171, 0, v171
	v_fmac_f32_e32 v169, v48, v170
	v_fmac_f32_e32 v169, v49, v171
	v_max_f32_e32 v173, 0, v173
	v_max_f32_e32 v172, 0, v172
	v_mul_f32_e32 v173, v59, v173
	v_max_f32_e32 v174, 0, v174
	v_fmac_f32_e32 v173, v58, v172
	v_max_f32_e32 v175, 0, v175
	v_fmac_f32_e32 v173, v60, v174
	v_fmac_f32_e32 v173, v61, v175
	v_max_f32_e32 v177, 0, v177
	v_max_f32_e32 v176, 0, v176
	v_permlane16_swap_b32_e32 v169, v173
	v_add_f32_e32 v200, v169, v173
	v_cvt_f16_f32_e32 v200, v200
	v_bfe_i32 v202, v200, 15, 1
	v_bitop3_b16 v200, v202, v200, s71 bitop3:0x36
	ds_write_b16 v210, v200
	v_mul_f32_e32 v177, v71, v177
	v_max_f32_e32 v178, 0, v178
	v_fmac_f32_e32 v177, v70, v176
	v_max_f32_e32 v179, 0, v179
	v_fmac_f32_e32 v177, v72, v178
	v_fmac_f32_e32 v177, v73, v179
	v_max_f32_e32 v181, 0, v181
	v_max_f32_e32 v180, 0, v180
	v_mul_f32_e32 v181, v83, v181
	v_max_f32_e32 v182, 0, v182
	v_fmac_f32_e32 v181, v82, v180
	v_max_f32_e32 v183, 0, v183
	v_fmac_f32_e32 v181, v84, v182
	v_fmac_f32_e32 v181, v85, v183
	s_nop 1
	v_permlane16_swap_b32_e32 v177, v181
	v_add_f32_e32 v201, v177, v181
	v_cvt_f16_f32_e32 v201, v201
	v_bfe_i32 v202, v201, 15, 1
	v_bitop3_b16 v201, v202, v201, s71 bitop3:0x36
	ds_write_b16 v211, v201
	s_waitcnt vmcnt(6)
	v_mfma_f32_16x16x32_bf16 v[168:171], v[38:41], v[18:21], 0
	v_mfma_f32_16x16x32_bf16 v[172:175], v[50:53], v[18:21], 0
	v_mfma_f32_16x16x32_bf16 v[176:179], v[62:65], v[18:21], 0
	v_mfma_f32_16x16x32_bf16 v[180:183], v[74:77], v[18:21], 0
	v_mfma_f32_16x16x32_bf16 v[168:171], v[42:45], v[14:17], v[168:171]
	v_mfma_f32_16x16x32_bf16 v[172:175], v[54:57], v[14:17], v[172:175]
	v_mfma_f32_16x16x32_bf16 v[176:179], v[66:69], v[14:17], v[176:179]
	v_mfma_f32_16x16x32_bf16 v[180:183], v[78:81], v[14:17], v[180:183]
	s_cbranch_vccnz .Lsc_np2
	global_load_dwordx4 v[18:21], v[208:209], off
	global_load_dwordx4 v[14:17], v[208:209], off offset:64
	s_branch .Lsc_c2

.Lsc_c2:
	v_max_f32_e32 v185, 0, v185
	v_max_f32_e32 v184, 0, v184
	v_mul_f32_e32 v185, v47, v185
	v_max_f32_e32 v186, 0, v186
	v_fmac_f32_e32 v185, v46, v184
	v_max_f32_e32 v187, 0, v187
	v_fmac_f32_e32 v185, v48, v186
	v_fmac_f32_e32 v185, v49, v187
	v_max_f32_e32 v189, 0, v189
	v_max_f32_e32 v188, 0, v188
	v_mul_f32_e32 v189, v59, v189
	v_max_f32_e32 v190, 0, v190
	v_fmac_f32_e32 v189, v58, v188
	v_max_f32_e32 v191, 0, v191
	v_fmac_f32_e32 v189, v60, v190
	v_fmac_f32_e32 v189, v61, v191
	v_max_f32_e32 v193, 0, v193
	v_max_f32_e32 v192, 0, v192
	v_permlane16_swap_b32_e32 v185, v189
	v_add_f32_e32 v200, v185, v189
	v_cvt_f16_f32_e32 v200, v200
	v_bfe_i32 v202, v200, 15, 1
	v_bitop3_b16 v200, v202, v200, s71 bitop3:0x36
	ds_write_b16 v210, v200 offset:32
	v_mul_f32_e32 v193, v71, v193
	v_max_f32_e32 v194, 0, v194
	v_fmac_f32_e32 v193, v70, v192
	v_max_f32_e32 v195, 0, v195
	v_fmac_f32_e32 v193, v72, v194
	v_fmac_f32_e32 v193, v73, v195
	v_max_f32_e32 v197, 0, v197
	v_max_f32_e32 v196, 0, v196
	v_mul_f32_e32 v197, v83, v197
	v_max_f32_e32 v198, 0, v198
	v_fmac_f32_e32 v197, v82, v196
	v_max_f32_e32 v199, 0, v199
	v_fmac_f32_e32 v197, v84, v198
	v_fmac_f32_e32 v197, v85, v199
	s_nop 1
	v_permlane16_swap_b32_e32 v193, v197
	v_add_f32_e32 v201, v193, v197
	v_cvt_f16_f32_e32 v201, v201
	v_bfe_i32 v202, v201, 15, 1
	v_bitop3_b16 v201, v202, v201, s71 bitop3:0x36
	ds_write_b16 v211, v201 offset:32
	s_waitcnt vmcnt(6)
	v_mfma_f32_16x16x32_bf16 v[184:187], v[38:41], v[10:13], 0
	v_mfma_f32_16x16x32_bf16 v[188:191], v[50:53], v[10:13], 0
	v_mfma_f32_16x16x32_bf16 v[192:195], v[62:65], v[10:13], 0
	v_mfma_f32_16x16x32_bf16 v[196:199], v[74:77], v[10:13], 0
	v_mfma_f32_16x16x32_bf16 v[184:187], v[42:45], v[6:9], v[184:187]
	v_mfma_f32_16x16x32_bf16 v[188:191], v[54:57], v[6:9], v[188:191]
	v_mfma_f32_16x16x32_bf16 v[192:195], v[66:69], v[6:9], v[192:195]
	v_mfma_f32_16x16x32_bf16 v[196:199], v[78:81], v[6:9], v[196:199]
	s_cbranch_vccnz .Lsc_np3
	global_load_dwordx4 v[10:13], v[208:209], off offset:2048
	global_load_dwordx4 v[6:9], v[208:209], off offset:2112
	s_branch .Lsc_c3

; __device__ void phase2(const Params& p, unsigned char* smem) {
;     ...
;       for (; c < nchunk; c += 8) {
;         bf16x8 cA0 = nA0, cB0 = nB0, cA1 = nA1, cB1 = nB1, cA2 = nA2, cB2 = nB2, cA3 = nA3, cB3 = nB3;
;         if (c + 8 < nchunk) P2_LOADCHUNK(c + 8, nA0, nB0, nA1, nB1, nA2, nB2, nA3, nB3)
;         __builtin_amdgcn_sched_barrier(0);
;         P2_SCORE(cA0, cB0, c * 4 + 0)
;         P2_SCORE(cA1, cB1, c * 4 + 1)
;         P2_SCORE(cA2, cB2, c * 4 + 2)
;         P2_SCORE(cA3, cB3, c * 4 + 3)
;       }
.Lsc_c3:
	v_max_f32_e32 v169, 0, v169
	v_max_f32_e32 v168, 0, v168
	v_mul_f32_e32 v169, v47, v169
	v_max_f32_e32 v170, 0, v170
	v_fmac_f32_e32 v169, v46, v168
	v_max_f32_e32 v171, 0, v171
	v_fmac_f32_e32 v169, v48, v170
	v_fmac_f32_e32 v169, v49, v171
	v_max_f32_e32 v173, 0, v173
	v_max_f32_e32 v172, 0, v172
	v_mul_f32_e32 v173, v59, v173
	v_max_f32_e32 v174, 0, v174
	v_fmac_f32_e32 v173, v58, v172
	v_max_f32_e32 v175, 0, v175
	v_fmac_f32_e32 v173, v60, v174
	v_fmac_f32_e32 v173, v61, v175
	v_max_f32_e32 v177, 0, v177
	v_max_f32_e32 v176, 0, v176
	v_permlane16_swap_b32_e32 v169, v173
	v_add_f32_e32 v200, v169, v173
	v_cvt_f16_f32_e32 v200, v200
	v_bfe_i32 v202, v200, 15, 1
	v_bitop3_b16 v200, v202, v200, s71 bitop3:0x36
	ds_write_b16 v210, v200 offset:64
	v_mul_f32_e32 v177, v71, v177
	v_max_f32_e32 v178, 0, v178
	v_fmac_f32_e32 v177, v70, v176
	v_max_f32_e32 v179, 0, v179
	v_fmac_f32_e32 v177, v72, v178
	v_fmac_f32_e32 v177, v73, v179
	v_max_f32_e32 v181, 0, v181
	v_max_f32_e32 v180, 0, v180
	v_mul_f32_e32 v181, v83, v181
	v_max_f32_e32 v182, 0, v182
	v_fmac_f32_e32 v181, v82, v180
	v_max_f32_e32 v183, 0, v183
	v_fmac_f32_e32 v181, v84, v182
	v_fmac_f32_e32 v181, v85, v183
	s_nop 1
	v_permlane16_swap_b32_e32 v177, v181
	v_add_f32_e32 v201, v177, v181
	v_cvt_f16_f32_e32 v201, v201
	v_bfe_i32 v202, v201, 15, 1
	v_bitop3_b16 v201, v202, v201, s71 bitop3:0x36
	ds_write_b16 v211, v201 offset:64
	v_max_f32_e32 v185, 0, v185
	v_max_f32_e32 v184, 0, v184
	v_mul_f32_e32 v185, v47, v185
	v_max_f32_e32 v186, 0, v186
	v_fmac_f32_e32 v185, v46, v184
	v_max_f32_e32 v187, 0, v187
	v_fmac_f32_e32 v185, v48, v186
	v_fmac_f32_e32 v185, v49, v187
	v_max_f32_e32 v189, 0, v189
	v_max_f32_e32 v188, 0, v188
	v_mul_f32_e32 v189, v59, v189
	v_max_f32_e32 v190, 0, v190
	v_fmac_f32_e32 v189, v58, v188
	v_max_f32_e32 v191, 0, v191
	v_fmac_f32_e32 v189, v60, v190
	v_fmac_f32_e32 v189, v61, v191
	v_max_f32_e32 v193, 0, v193
	v_max_f32_e32 v192, 0, v192
	v_permlane16_swap_b32_e32 v185, v189
	v_add_f32_e32 v200, v185, v189
	v_cvt_f16_f32_e32 v200, v200
	v_bfe_i32 v202, v200, 15, 1
	v_bitop3_b16 v200, v202, v200, s71 bitop3:0x36
	ds_write_b16 v210, v200 offset:96
	v_mul_f32_e32 v193, v71, v193
	v_max_f32_e32 v194, 0, v194
	v_fmac_f32_e32 v193, v70, v192
	v_max_f32_e32 v195, 0, v195
	v_fmac_f32_e32 v193, v72, v194
	v_fmac_f32_e32 v193, v73, v195
	v_max_f32_e32 v197, 0, v197
	v_max_f32_e32 v196, 0, v196
	v_mul_f32_e32 v197, v83, v197
	v_max_f32_e32 v198, 0, v198
	v_fmac_f32_e32 v197, v82, v196
	v_max_f32_e32 v199, 0, v199
	v_fmac_f32_e32 v197, v84, v198
	v_fmac_f32_e32 v197, v85, v199
	s_nop 1
	v_permlane16_swap_b32_e32 v193, v197
	v_add_f32_e32 v201, v193, v197
	v_cvt_f16_f32_e32 v201, v201
	v_bfe_i32 v202, v201, 15, 1
	v_bitop3_b16 v201, v202, v201, s71 bitop3:0x36
	ds_write_b16 v211, v201 offset:96
	v_lshl_add_u64 v[142:143], v[142:143], 0, s[60:61]
	v_lshl_add_u64 v[208:209], v[208:209], 0, s[60:61]
	v_add_u32_e32 v210, 0x400, v210
	v_add_u32_e32 v211, 0x400, v211
	s_add_i32 s40, s40, 8
	s_add_i32 s41, s41, 8
	s_cmp_lt_u32 s40, s47
	s_cbranch_scc1 .Lsc_loop
